# combined micro-edits on the best kernel: MLA gate cache-prefetch at last tile, SB second-block K-fragment prefetch, 64-bit accumulator zeroing at 5 GEMM sites
# speedup vs baseline: 1.0085x; 1.0085x over previous
.LBB0_185:
	s_ashr_i32 s45, s44, 31
	s_lshl_b64 s[46:47], s[44:45], 20
	s_add_u32 s46, s34, s46
	s_addc_u32 s47, s35, s47
	s_and_b64 s[48:49], s[0:1], exec
	s_cselect_b32 s45, s47, s53
	s_cselect_b32 s80, s46, s52
	s_ashr_i32 s43, s42, 31
	s_lshl_b64 s[48:49], s[42:43], 20
	s_add_u32 s48, s8, s48
	s_addc_u32 s49, s9, s49
	s_and_b64 s[56:57], s[0:1], exec
	s_cselect_b32 s43, s49, s55
	s_cselect_b32 s81, s48, s54
	s_add_u32 s52, s52, 0x80080
	s_addc_u32 s53, s53, 0
	s_add_u32 s82, s54, 0x100
	s_addc_u32 s83, s55, 0
	s_mov_b32 s86, -2
	v_mov_b64_e32 v[0:1], 0
	v_mov_b64_e32 v[2:3], 0
	v_mov_b64_e32 v[4:5], 0
	v_mov_b64_e32 v[6:7], 0
	v_mov_b64_e32 v[8:9], 0
	v_mov_b64_e32 v[10:11], 0
	v_mov_b64_e32 v[12:13], 0
	v_mov_b64_e32 v[14:15], 0
	v_mov_b64_e32 v[16:17], 0
	v_mov_b64_e32 v[18:19], 0
	v_mov_b64_e32 v[20:21], 0
	v_mov_b64_e32 v[22:23], 0
	v_mov_b64_e32 v[24:25], 0
	v_mov_b64_e32 v[26:27], 0
	v_mov_b64_e32 v[28:29], 0
	v_mov_b64_e32 v[30:31], 0
	v_mov_b64_e32 v[32:33], 0
	v_mov_b64_e32 v[34:35], 0
	v_mov_b64_e32 v[36:37], 0
	v_mov_b64_e32 v[38:39], 0
	v_mov_b64_e32 v[40:41], 0
	v_mov_b64_e32 v[42:43], 0
	v_mov_b64_e32 v[44:45], 0
	v_mov_b64_e32 v[46:47], 0
	v_mov_b64_e32 v[48:49], 0
	v_mov_b64_e32 v[50:51], 0
	v_mov_b64_e32 v[52:53], 0
	v_mov_b64_e32 v[54:55], 0
	v_mov_b64_e32 v[56:57], 0
	v_mov_b64_e32 v[58:59], 0
	v_mov_b64_e32 v[60:61], 0
	v_mov_b64_e32 v[62:63], 0
	v_mov_b64_e32 v[64:65], 0
	v_mov_b64_e32 v[66:67], 0
	v_mov_b64_e32 v[68:69], 0
	v_mov_b64_e32 v[70:71], 0
	v_mov_b64_e32 v[72:73], 0
	v_mov_b64_e32 v[74:75], 0
	v_mov_b64_e32 v[76:77], 0
	v_mov_b64_e32 v[78:79], 0
	v_mov_b64_e32 v[80:81], 0
	v_mov_b64_e32 v[82:83], 0
	v_mov_b64_e32 v[84:85], 0
	v_mov_b64_e32 v[86:87], 0
	v_mov_b64_e32 v[88:89], 0
	v_mov_b64_e32 v[90:91], 0
	v_mov_b64_e32 v[92:93], 0
	v_mov_b64_e32 v[94:95], 0
	v_mov_b64_e32 v[96:97], 0
	v_mov_b64_e32 v[98:99], 0
	v_mov_b64_e32 v[100:101], 0
	v_mov_b64_e32 v[102:103], 0
	v_mov_b64_e32 v[104:105], 0
	v_mov_b64_e32 v[106:107], 0
	v_mov_b64_e32 v[108:109], 0
	v_mov_b64_e32 v[110:111], 0
	v_mov_b64_e32 v[112:113], 0
	v_mov_b64_e32 v[114:115], 0
	v_mov_b64_e32 v[116:117], 0
	v_mov_b64_e32 v[118:119], 0
	v_mov_b64_e32 v[120:121], 0
	v_mov_b64_e32 v[122:123], 0
	v_mov_b64_e32 v[124:125], 0
	v_mov_b64_e32 v[126:127], 0

.LBB0_260:
	s_ashr_i32 s51, s50, 31
	s_lshl_b64 s[52:53], s[50:51], 20
	s_add_u32 s52, s63, s52
	s_addc_u32 s53, s64, s53
	s_and_b64 s[54:55], s[46:47], exec
	s_cselect_b32 s5, s53, s57
	s_cselect_b32 s9, s52, s56
	s_ashr_i32 s49, s48, 31
	s_lshl_b64 s[54:55], s[48:49], 20
	s_add_u32 s54, s72, s54
	s_addc_u32 s55, s73, s55
	s_and_b64 s[60:61], s[46:47], exec
	s_cselect_b32 s49, s55, s59
	s_cselect_b32 s51, s54, s58
	s_add_u32 s56, s56, 0x80080
	s_addc_u32 s57, s57, 0
	s_add_u32 s88, s58, 0x100
	s_addc_u32 s89, s59, 0
	s_mov_b32 s90, -2
	v_mov_b64_e32 v[0:1], 0
	v_mov_b64_e32 v[2:3], 0
	v_mov_b64_e32 v[4:5], 0
	v_mov_b64_e32 v[6:7], 0
	v_mov_b64_e32 v[8:9], 0
	v_mov_b64_e32 v[10:11], 0
	v_mov_b64_e32 v[12:13], 0
	v_mov_b64_e32 v[14:15], 0
	v_mov_b64_e32 v[16:17], 0
	v_mov_b64_e32 v[18:19], 0
	v_mov_b64_e32 v[20:21], 0
	v_mov_b64_e32 v[22:23], 0
	v_mov_b64_e32 v[24:25], 0
	v_mov_b64_e32 v[26:27], 0
	v_mov_b64_e32 v[28:29], 0
	v_mov_b64_e32 v[30:31], 0
	v_mov_b64_e32 v[32:33], 0
	v_mov_b64_e32 v[34:35], 0
	v_mov_b64_e32 v[36:37], 0
	v_mov_b64_e32 v[38:39], 0
	v_mov_b64_e32 v[40:41], 0
	v_mov_b64_e32 v[42:43], 0
	v_mov_b64_e32 v[44:45], 0
	v_mov_b64_e32 v[46:47], 0
	v_mov_b64_e32 v[48:49], 0
	v_mov_b64_e32 v[50:51], 0
	v_mov_b64_e32 v[52:53], 0
	v_mov_b64_e32 v[54:55], 0
	v_mov_b64_e32 v[56:57], 0
	v_mov_b64_e32 v[58:59], 0
	v_mov_b64_e32 v[60:61], 0
	v_mov_b64_e32 v[62:63], 0
	v_mov_b64_e32 v[64:65], 0
	v_mov_b64_e32 v[66:67], 0
	v_mov_b64_e32 v[68:69], 0
	v_mov_b64_e32 v[70:71], 0
	v_mov_b64_e32 v[72:73], 0
	v_mov_b64_e32 v[74:75], 0
	v_mov_b64_e32 v[76:77], 0
	v_mov_b64_e32 v[78:79], 0
	v_mov_b64_e32 v[80:81], 0
	v_mov_b64_e32 v[82:83], 0
	v_mov_b64_e32 v[84:85], 0
	v_mov_b64_e32 v[86:87], 0
	v_mov_b64_e32 v[88:89], 0
	v_mov_b64_e32 v[90:91], 0
	v_mov_b64_e32 v[92:93], 0
	v_mov_b64_e32 v[94:95], 0
	v_mov_b64_e32 v[96:97], 0
	v_mov_b64_e32 v[98:99], 0
	v_mov_b64_e32 v[100:101], 0
	v_mov_b64_e32 v[102:103], 0
	v_mov_b64_e32 v[104:105], 0
	v_mov_b64_e32 v[106:107], 0
	v_mov_b64_e32 v[108:109], 0
	v_mov_b64_e32 v[110:111], 0
	v_mov_b64_e32 v[112:113], 0
	v_mov_b64_e32 v[114:115], 0
	v_mov_b64_e32 v[116:117], 0
	v_mov_b64_e32 v[118:119], 0
	v_mov_b64_e32 v[120:121], 0
	v_mov_b64_e32 v[122:123], 0
	v_mov_b64_e32 v[124:125], 0
	v_mov_b64_e32 v[126:127], 0

.LBB0_342:
	s_mul_i32 s44, s65, 0xa000
	s_add_i32 s44, s44, 0
	v_add_u32_e32 v64, s44, v141
	v_add3_u32 v65, s44, v143, v144
	s_add_i32 s44, s62, 32
	s_cmp_ge_i32 s44, s60
	s_cselect_b64 s[44:45], -1, 0
	s_or_b64 s[44:45], s[44:45], s[42:43]
	s_and_b64 vcc, exec, s[44:45]
	v_add_u32_e32 v149, v64, v120
	v_add_u32_e32 v147, v65, v145
	v_add_u32_e32 v148, s62, v142
	ds_read_b128 v[180:183], v149
	ds_read_b128 v[184:187], v149 offset:32
	ds_read_b128 v[188:191], v149 offset:64
	s_cbranch_vccnz .LBB0_344
	ds_read_b128 v[64:67], v149 offset:8704
	ds_read_b128 v[112:115], v149 offset:8736
	ds_read_b128 v[116:119], v149 offset:8768
	s_add_i32 s42, s62, 63
	s_cmp_lt_i32 s42, s56
	s_cselect_b64 s[42:43], -1, 0
	s_waitcnt lgkmcnt(0)
	v_mfma_f32_32x32x16_bf16 v[64:79], v[64:67], v[80:83], 0
	ds_read_b128 v[150:153], v149 offset:8800
	v_mfma_f32_32x32x16_bf16 v[64:79], v[112:115], v[84:87], v[64:79]
	ds_read_b128 v[112:115], v149 offset:8832
	v_mfma_f32_32x32x16_bf16 v[64:79], v[116:119], v[88:91], v[64:79]
	ds_read_b128 v[116:119], v149 offset:8864
	s_waitcnt lgkmcnt(0)
	v_mfma_f32_32x32x16_bf16 v[64:79], v[150:153], v[92:95], v[64:79]
	ds_read_b128 v[150:153], v149 offset:8896
	v_mfma_f32_32x32x16_bf16 v[64:79], v[112:115], v[96:99], v[64:79]
	ds_read_b128 v[112:115], v149 offset:8928
	v_mfma_f32_32x32x16_bf16 v[64:79], v[116:119], v[100:103], v[64:79]
	s_waitcnt lgkmcnt(0)
	v_mfma_f32_32x32x16_bf16 v[64:79], v[150:153], v[104:107], v[64:79]
	v_mfma_f32_32x32x16_bf16 v[64:79], v[112:115], v[108:111], v[64:79]
	ds_read_b64_tr_b16 v[116:117], v147 offset:27648
	ds_read_b64_tr_b16 v[118:119], v147 offset:30208
	ds_read_b64_tr_b16 v[114:115], v147 offset:30272
	ds_read_b64_tr_b16 v[112:113], v147 offset:27712
	s_nop 7
	v_max_f32_e32 v64, v64, v64
	v_min_f32_e32 v64, 0x42a00000, v64
	v_exp_f32_e32 v64, v64
	v_max_f32_e32 v65, v65, v65
	v_min_f32_e32 v65, 0x42a00000, v65
	v_exp_f32_e32 v65, v65
	v_add_f32_e32 v136, 1.0, v64
	v_rcp_f32_e32 v136, v136
	v_add_u32_e32 v137, 32, v148
	v_cmp_lt_i32_e32 vcc, v137, v122
	s_or_b64 vcc, s[42:43], vcc
	v_mul_f32_e32 v64, v64, v136
	v_cndmask_b32_e32 v150, 0, v64, vcc
	v_add_u32_e32 v64, 33, v148
	v_add_f32_e32 v137, 1.0, v65
	v_cndmask_b32_e32 v136, 1.0, v136, vcc
	v_cmp_lt_i32_e32 vcc, v64, v122
	v_max_f32_e32 v64, v66, v66
	v_rcp_f32_e32 v137, v137
	v_min_f32_e32 v64, 0x42a00000, v64
	v_exp_f32_e32 v66, v64
	s_or_b64 vcc, s[42:43], vcc
	v_mul_f32_e32 v65, v65, v137
	v_cndmask_b32_e32 v151, 0, v65, vcc
	v_add_f32_e32 v65, 1.0, v66
	v_max_f32_e32 v67, v67, v67
	v_rcp_f32_e32 v65, v65
	v_min_f32_e32 v67, 0x42a00000, v67
	v_exp_f32_e32 v67, v67
	v_cndmask_b32_e32 v64, 1.0, v137, vcc
	v_mul_f32_e32 v137, v66, v65
	v_add_u32_e32 v66, 34, v148
	v_cmp_lt_i32_e32 vcc, v66, v122
	v_add_f32_e32 v66, 1.0, v67
	v_rcp_f32_e32 v152, v66
	s_or_b64 vcc, s[42:43], vcc
	v_cndmask_b32_e32 v66, 1.0, v65, vcc
	v_cndmask_b32_e32 v153, 0, v137, vcc
	v_mul_f32_e32 v65, v67, v152
	v_add_u32_e32 v67, 35, v148
	v_cmp_lt_i32_e32 vcc, v67, v122
	v_max_f32_e32 v67, v68, v68
	v_min_f32_e32 v67, 0x42a00000, v67
	v_max_f32_e32 v69, v69, v69
	v_exp_f32_e32 v67, v67
	v_min_f32_e32 v69, 0x42a00000, v69
	v_exp_f32_e32 v69, v69
	s_or_b64 vcc, s[42:43], vcc
	v_cndmask_b32_e32 v68, 1.0, v152, vcc
	v_cndmask_b32_e32 v152, 0, v65, vcc
	v_add_f32_e32 v65, 1.0, v67
	v_add_u32_e32 v137, 40, v148
	v_rcp_f32_e32 v65, v65
	v_cmp_lt_i32_e32 vcc, v137, v122
	v_add_f32_e32 v137, 1.0, v69
	v_rcp_f32_e32 v137, v137
	v_mul_f32_e32 v67, v67, v65
	s_or_b64 vcc, s[42:43], vcc
	v_cndmask_b32_e32 v154, 0, v67, vcc
	v_mul_f32_e32 v67, v69, v137
	v_add_u32_e32 v69, 41, v148
	v_cndmask_b32_e32 v65, 1.0, v65, vcc
	v_cmp_lt_i32_e32 vcc, v69, v122
	v_max_f32_e32 v69, v70, v70
	v_min_f32_e32 v69, 0x42a00000, v69
	v_exp_f32_e32 v69, v69
	v_max_f32_e32 v70, v71, v71
	v_min_f32_e32 v70, 0x42a00000, v70
	s_or_b64 vcc, s[42:43], vcc
	v_exp_f32_e32 v70, v70
	v_cndmask_b32_e32 v156, 0, v67, vcc
	v_add_f32_e32 v67, 1.0, v69
	v_rcp_f32_e32 v67, v67
	v_add_u32_e32 v71, 42, v148
	v_cndmask_b32_e32 v155, 1.0, v137, vcc
	v_cmp_lt_i32_e32 vcc, v71, v122
	v_add_f32_e32 v71, 1.0, v70
	v_rcp_f32_e32 v71, v71
	v_mul_f32_e32 v69, v69, v67
	s_or_b64 vcc, s[42:43], vcc
	v_cndmask_b32_e32 v158, 0, v69, vcc
	v_add_u32_e32 v69, 43, v148
	v_cndmask_b32_e32 v157, 1.0, v67, vcc
	v_cmp_lt_i32_e32 vcc, v69, v122
	v_max_f32_e32 v69, v72, v72
	v_mul_f32_e32 v67, v70, v71
	v_min_f32_e32 v69, 0x42a00000, v69
	v_max_f32_e32 v70, v73, v73
	v_exp_f32_e32 v69, v69
	v_min_f32_e32 v70, 0x42a00000, v70
	v_exp_f32_e32 v70, v70
	s_or_b64 vcc, s[42:43], vcc
	v_cndmask_b32_e32 v159, 1.0, v71, vcc
	v_cndmask_b32_e32 v160, 0, v67, vcc
	v_add_f32_e32 v67, 1.0, v69
	v_add_u32_e32 v71, 48, v148
	v_rcp_f32_e32 v67, v67
	v_cmp_lt_i32_e32 vcc, v71, v122
	v_add_f32_e32 v71, 1.0, v70
	v_rcp_f32_e32 v71, v71
	v_mul_f32_e32 v69, v69, v67
	s_or_b64 vcc, s[42:43], vcc
	v_cndmask_b32_e32 v72, 0, v69, vcc
	v_mul_f32_e32 v69, v70, v71
	v_add_u32_e32 v70, 49, v148
	v_cndmask_b32_e32 v67, 1.0, v67, vcc
	v_cmp_lt_i32_e32 vcc, v70, v122
	v_max_f32_e32 v70, v74, v74
	v_max_f32_e32 v74, v75, v75
	v_min_f32_e32 v70, 0x42a00000, v70
	v_min_f32_e32 v74, 0x42a00000, v74
	v_exp_f32_e32 v70, v70
	v_exp_f32_e32 v74, v74
	s_or_b64 vcc, s[42:43], vcc
	v_add_u32_e32 v75, 50, v148
	v_cndmask_b32_e32 v71, 1.0, v71, vcc
	v_cndmask_b32_e32 v73, 0, v69, vcc
	v_add_f32_e32 v69, 1.0, v70
	v_cmp_lt_i32_e32 vcc, v75, v122
	v_add_f32_e32 v75, 1.0, v74
	v_rcp_f32_e32 v69, v69
	v_rcp_f32_e32 v75, v75
	s_or_b64 vcc, s[42:43], vcc
	v_max_f32_e32 v77, v77, v77
	v_mul_f32_e32 v70, v70, v69
	v_cndmask_b32_e32 v161, 1.0, v69, vcc
	v_mul_f32_e32 v69, v74, v75
	v_add_u32_e32 v74, 51, v148
	v_cndmask_b32_e32 v70, 0, v70, vcc
	v_cmp_lt_i32_e32 vcc, v74, v122
	v_max_f32_e32 v74, v76, v76
	v_min_f32_e32 v74, 0x42a00000, v74
	v_exp_f32_e32 v74, v74
	v_min_f32_e32 v77, 0x42a00000, v77
	s_or_b64 vcc, s[42:43], vcc
	v_exp_f32_e32 v77, v77
	v_cndmask_b32_e32 v76, 0, v69, vcc
	v_add_f32_e32 v69, 1.0, v74
	v_rcp_f32_e32 v69, v69
	v_add_u32_e32 v137, 56, v148
	v_max_f32_e32 v78, v78, v78
	v_cndmask_b32_e32 v75, 1.0, v75, vcc
	v_cmp_lt_i32_e32 vcc, v137, v122
	v_add_f32_e32 v137, 1.0, v77
	v_min_f32_e32 v78, 0x42a00000, v78
	v_rcp_f32_e32 v137, v137
	v_exp_f32_e32 v78, v78
	v_mul_f32_e32 v74, v74, v69
	s_or_b64 vcc, s[42:43], vcc
	v_add_u32_e32 v162, 57, v148
	v_cndmask_b32_e32 v69, 1.0, v69, vcc
	v_cndmask_b32_e32 v74, 0, v74, vcc
	v_cmp_lt_i32_e32 vcc, v162, v122
	s_or_b64 vcc, s[42:43], vcc
	v_mul_f32_e32 v77, v77, v137
	v_cndmask_b32_e32 v162, 1.0, v137, vcc
	v_add_f32_e32 v137, 1.0, v78
	v_rcp_f32_e32 v137, v137
	v_max_f32_e32 v79, v79, v79
	v_add_u32_e32 v163, 58, v148
	v_cndmask_b32_e32 v77, 0, v77, vcc
	v_min_f32_e32 v79, 0x42a00000, v79
	v_cmp_lt_i32_e32 vcc, v163, v122
	v_exp_f32_e32 v79, v79
	s_or_b64 vcc, s[42:43], vcc
	v_mul_f32_e32 v78, v78, v137
	v_cndmask_b32_e32 v164, 1.0, v137, vcc
	v_add_u32_e32 v137, 59, v148
	v_cndmask_b32_e32 v78, 0, v78, vcc
	v_cmp_lt_i32_e32 vcc, v137, v122
	v_mul_f32_e32 v65, v65, v155
	v_mul_f32_e32 v137, v157, v159
	v_mul_f32_e32 v137, v65, v137
	v_add_f32_e32 v163, 1.0, v79
	v_mov_b32_e32 v65, v137
	v_mov_b32_e32 v165, v137
	v_rcp_f32_e32 v163, v163
	s_nop 0
	v_permlane32_swap_b32_e32 v65, v165
	v_cndmask_b32_e64 v65, v65, v165, s[0:1]
	v_mul_f32_e32 v67, v67, v71
	v_mul_f32_e32 v165, v161, v75
	v_mul_f32_e32 v67, v67, v165
	s_or_b64 vcc, s[42:43], vcc
	v_mov_b32_e32 v165, v67
	v_mov_b32_e32 v166, v67
	v_mul_f32_e32 v79, v79, v163
	v_cndmask_b32_e32 v163, 1.0, v163, vcc
	v_permlane32_swap_b32_e32 v165, v166
	v_cndmask_b32_e64 v165, v165, v166, s[0:1]
	v_mul_f32_e32 v69, v69, v162
	v_mul_f32_e32 v166, v164, v163
	v_mul_f32_e32 v69, v69, v166
	v_mov_b32_e32 v166, v69
	v_mov_b32_e32 v167, v69
	s_nop 1
	v_permlane32_swap_b32_e32 v166, v167
	v_cndmask_b32_e64 v166, v166, v167, s[0:1]
	v_cndmask_b32_e64 v167, 1.0, v166, s[0:1]
	v_mul_f32_e32 v69, v69, v166
	v_mul_f32_e32 v167, v146, v167
	v_mul_f32_e32 v69, v146, v69
	v_cndmask_b32_e64 v146, 1.0, v165, s[0:1]
	v_mul_f32_e32 v146, v146, v69
	v_mul_f32_e32 v163, v163, v167
	v_mul_f32_e32 v75, v75, v146
	v_mul_f32_e32 v164, v164, v163
	v_mul_f32_e32 v161, v161, v75
	v_mul_f32_e32 v162, v162, v164
	v_mul_f32_e32 v71, v71, v161
	v_mul_f32_e32 v67, v67, v165
	v_mul_f32_e32 v74, v74, v162
	v_mul_f32_e32 v75, v70, v75
	v_mul_f32_e32 v161, v73, v161
	v_mul_f32_e32 v162, v72, v71
	v_pk_mul_f32 v[70:71], v[66:67], v[68:69]
	v_pk_mul_f32 v[72:73], v[136:137], v[64:65]
	v_mul_f32_e32 v76, v76, v146
	v_pk_mul_f32 v[72:73], v[72:73], v[70:71]
	v_cndmask_b32_e64 v146, 1.0, v65, s[0:1]
	v_mov_b32_e32 v65, v72
	v_mov_b32_e32 v67, v72
	s_nop 1
	v_permlane32_swap_b32_e32 v65, v67
	v_cndmask_b32_e64 v65, v65, v67, s[0:1]
	v_cndmask_b32_e64 v136, 1.0, v65, s[0:1]
	v_mul_f32_e32 v67, v146, v71
	v_mul_f32_e32 v136, v136, v73
	v_mul_f32_e32 v69, v159, v67
	v_mul_f32_e32 v68, v68, v136
	v_mul_f32_e32 v70, v157, v69
	v_mul_f32_e32 v66, v66, v68
	v_cndmask_b32_e32 v79, 0, v79, vcc
	v_mul_f32_e32 v71, v155, v70
	v_mul_f32_e32 v64, v64, v66
	v_mul_f32_e32 v65, v72, v65
	v_mul_f32_e32 v79, v79, v167
	v_mul_f32_e32 v78, v78, v163
	v_mul_f32_e32 v77, v77, v164
	v_mul_f32_e32 v67, v160, v67
	v_mul_f32_e32 v69, v158, v69
	v_mul_f32_e32 v70, v156, v70
	v_mul_f32_e32 v71, v154, v71
	v_mul_f32_e32 v136, v152, v136
	v_mul_f32_e32 v68, v153, v68
	v_mul_f32_e32 v66, v151, v66
	v_mul_f32_e32 v64, v150, v64
	v_mul_f32_e32 v146, v65, v73
	v_cvt_pk_bf16_f32 v64, v64, v66
	v_cvt_pk_bf16_f32 v65, v68, v136
	v_cvt_pk_bf16_f32 v66, v71, v70
	v_cvt_pk_bf16_f32 v67, v69, v67
	v_cvt_pk_bf16_f32 v68, v162, v161
	v_cvt_pk_bf16_f32 v69, v75, v76
	v_cvt_pk_bf16_f32 v70, v74, v77
	v_cvt_pk_bf16_f32 v71, v78, v79
	v_cmp_gt_f32_e32 vcc, s55, v146
	s_waitcnt lgkmcnt(0)
	v_mfma_f32_32x32x16_bf16 v[48:63], v[116:119], v[64:67], v[48:63]
	ds_read_b64_tr_b16 v[72:73], v147 offset:27776
	ds_read_b64_tr_b16 v[74:75], v147 offset:30336
	v_mfma_f32_32x32x16_bf16 v[32:47], v[112:115], v[64:67], v[32:47]
	ds_read_b64_tr_b16 v[76:77], v147 offset:27840
	ds_read_b64_tr_b16 v[78:79], v147 offset:30400
	s_waitcnt lgkmcnt(0)
	v_mfma_f32_32x32x16_bf16 v[16:31], v[72:75], v[64:67], v[16:31]
	ds_read_b64_tr_b16 v[112:113], v147 offset:32768
	ds_read_b64_tr_b16 v[114:115], v147 offset:35328
	v_mfma_f32_32x32x16_bf16 v[0:15], v[76:79], v[64:67], v[0:15]
	ds_read_b64_tr_b16 v[72:73], v147 offset:32832
	ds_read_b64_tr_b16 v[74:75], v147 offset:35392
	s_waitcnt lgkmcnt(0)
	v_mfma_f32_32x32x16_bf16 v[48:63], v[112:115], v[68:71], v[48:63]
	ds_read_b64_tr_b16 v[64:65], v147 offset:32896
	ds_read_b64_tr_b16 v[66:67], v147 offset:35456
	v_mfma_f32_32x32x16_bf16 v[32:47], v[72:75], v[68:71], v[32:47]
	ds_read_b64_tr_b16 v[76:77], v147 offset:32960
	ds_read_b64_tr_b16 v[78:79], v147 offset:35520
	s_waitcnt lgkmcnt(0)
	v_mfma_f32_32x32x16_bf16 v[16:31], v[64:67], v[68:71], v[16:31]
	v_mfma_f32_32x32x16_bf16 v[0:15], v[76:79], v[68:71], v[0:15]
	s_cmp_eq_u64 vcc, exec
	s_cselect_b64 s[42:43], -1, 0
.LBB0_344:
	s_cmp_ge_i32 s62, s60
	s_cselect_b64 s[44:45], -1, 0
	s_or_b64 s[44:45], s[44:45], s[42:43]
	s_and_b64 vcc, exec, s[44:45]
	s_cbranch_vccnz .LBB0_348
	ds_read_b128 v[150:153], v149 offset:96
	ds_read_b128 v[112:115], v149 offset:128
	s_add_i32 s42, s62, 31
	s_cmp_lt_i32 s42, s56
	s_cselect_b64 s[42:43], -1, 0
	s_waitcnt lgkmcnt(2)
	v_mfma_f32_32x32x16_bf16 v[64:79], v[180:183], v[80:83], 0
	v_mfma_f32_32x32x16_bf16 v[64:79], v[184:187], v[84:87], v[64:79]
	v_mfma_f32_32x32x16_bf16 v[64:79], v[188:191], v[88:91], v[64:79]
	ds_read_b128 v[116:119], v149 offset:160
	s_waitcnt lgkmcnt(0)
	v_mfma_f32_32x32x16_bf16 v[64:79], v[150:153], v[92:95], v[64:79]
	ds_read_b128 v[150:153], v149 offset:192
	v_mfma_f32_32x32x16_bf16 v[64:79], v[112:115], v[96:99], v[64:79]
	ds_read_b128 v[112:115], v149 offset:224
	v_mfma_f32_32x32x16_bf16 v[64:79], v[116:119], v[100:103], v[64:79]
	s_waitcnt lgkmcnt(0)
	v_mfma_f32_32x32x16_bf16 v[64:79], v[150:153], v[104:107], v[64:79]
	v_mfma_f32_32x32x16_bf16 v[64:79], v[112:115], v[108:111], v[64:79]
	ds_read_b64_tr_b16 v[116:117], v147 offset:17408
	ds_read_b64_tr_b16 v[118:119], v147 offset:19968
	ds_read_b64_tr_b16 v[114:115], v147 offset:20032
	ds_read_b64_tr_b16 v[112:113], v147 offset:17472
	s_nop 7
	v_max_f32_e32 v64, v64, v64
	v_min_f32_e32 v64, 0x42a00000, v64
	v_exp_f32_e32 v64, v64
	v_max_f32_e32 v65, v65, v65
	v_min_f32_e32 v65, 0x42a00000, v65
	v_exp_f32_e32 v65, v65
	v_add_f32_e32 v136, 1.0, v64
	v_rcp_f32_e32 v136, v136
	v_cmp_lt_i32_e32 vcc, v148, v122
	s_or_b64 vcc, s[42:43], vcc
	v_add_f32_e32 v137, 1.0, v65
	v_mul_f32_e32 v64, v64, v136
	v_cndmask_b32_e32 v149, 0, v64, vcc
	v_add_u32_e32 v64, 1, v148
	v_cndmask_b32_e32 v136, 1.0, v136, vcc
	v_cmp_lt_i32_e32 vcc, v64, v122
	v_max_f32_e32 v64, v66, v66
	v_rcp_f32_e32 v137, v137
	v_min_f32_e32 v64, 0x42a00000, v64
	v_exp_f32_e32 v66, v64
	s_or_b64 vcc, s[42:43], vcc
	v_mul_f32_e32 v65, v65, v137
	v_cndmask_b32_e32 v150, 0, v65, vcc
	v_add_f32_e32 v65, 1.0, v66
	v_max_f32_e32 v67, v67, v67
	v_rcp_f32_e32 v65, v65
	v_min_f32_e32 v67, 0x42a00000, v67
	v_exp_f32_e32 v67, v67
	v_cndmask_b32_e32 v64, 1.0, v137, vcc
	v_mul_f32_e32 v137, v66, v65
	v_add_u32_e32 v66, 2, v148
	v_cmp_lt_i32_e32 vcc, v66, v122
	v_add_f32_e32 v66, 1.0, v67
	v_rcp_f32_e32 v151, v66
	s_or_b64 vcc, s[42:43], vcc
	v_cndmask_b32_e32 v66, 1.0, v65, vcc
	v_cndmask_b32_e32 v152, 0, v137, vcc
	v_mul_f32_e32 v65, v67, v151
	v_add_u32_e32 v67, 3, v148
	v_cmp_lt_i32_e32 vcc, v67, v122
	v_max_f32_e32 v67, v68, v68
	v_min_f32_e32 v67, 0x42a00000, v67
	v_max_f32_e32 v69, v69, v69
	v_exp_f32_e32 v67, v67
	v_min_f32_e32 v69, 0x42a00000, v69
	v_exp_f32_e32 v69, v69
	s_or_b64 vcc, s[42:43], vcc
	v_cndmask_b32_e32 v68, 1.0, v151, vcc
	v_cndmask_b32_e32 v151, 0, v65, vcc
	v_add_f32_e32 v65, 1.0, v67
	v_add_u32_e32 v137, 8, v148
	v_rcp_f32_e32 v65, v65
	v_cmp_lt_i32_e32 vcc, v137, v122
	v_add_f32_e32 v137, 1.0, v69
	v_rcp_f32_e32 v137, v137
	v_mul_f32_e32 v67, v67, v65
	s_or_b64 vcc, s[42:43], vcc
	v_cndmask_b32_e32 v153, 0, v67, vcc
	v_mul_f32_e32 v67, v69, v137
	v_add_u32_e32 v69, 9, v148
	v_cndmask_b32_e32 v65, 1.0, v65, vcc
	v_cmp_lt_i32_e32 vcc, v69, v122
	v_max_f32_e32 v69, v70, v70
	v_min_f32_e32 v69, 0x42a00000, v69
	v_exp_f32_e32 v69, v69
	v_max_f32_e32 v70, v71, v71
	v_min_f32_e32 v70, 0x42a00000, v70
	s_or_b64 vcc, s[42:43], vcc
	v_exp_f32_e32 v70, v70
	v_cndmask_b32_e32 v155, 0, v67, vcc
	v_add_f32_e32 v67, 1.0, v69
	v_rcp_f32_e32 v67, v67
	v_add_u32_e32 v71, 10, v148
	v_cndmask_b32_e32 v154, 1.0, v137, vcc
	v_cmp_lt_i32_e32 vcc, v71, v122
	v_add_f32_e32 v71, 1.0, v70
	v_rcp_f32_e32 v71, v71
	v_mul_f32_e32 v69, v69, v67
	s_or_b64 vcc, s[42:43], vcc
	v_cndmask_b32_e32 v157, 0, v69, vcc
	v_add_u32_e32 v69, 11, v148
	v_cndmask_b32_e32 v156, 1.0, v67, vcc
	v_cmp_lt_i32_e32 vcc, v69, v122
	v_max_f32_e32 v69, v72, v72
	v_mul_f32_e32 v67, v70, v71
	v_min_f32_e32 v69, 0x42a00000, v69
	v_max_f32_e32 v70, v73, v73
	v_exp_f32_e32 v69, v69
	v_min_f32_e32 v70, 0x42a00000, v70
	v_exp_f32_e32 v70, v70
	s_or_b64 vcc, s[42:43], vcc
	v_cndmask_b32_e32 v158, 1.0, v71, vcc
	v_cndmask_b32_e32 v159, 0, v67, vcc
	v_add_f32_e32 v67, 1.0, v69
	v_add_u32_e32 v71, 16, v148
	v_rcp_f32_e32 v67, v67
	v_cmp_lt_i32_e32 vcc, v71, v122
	v_add_f32_e32 v71, 1.0, v70
	v_rcp_f32_e32 v71, v71
	v_mul_f32_e32 v69, v69, v67
	s_or_b64 vcc, s[42:43], vcc
	v_cndmask_b32_e32 v72, 0, v69, vcc
	v_mul_f32_e32 v69, v70, v71
	v_add_u32_e32 v70, 17, v148
	v_cndmask_b32_e32 v67, 1.0, v67, vcc
	v_cmp_lt_i32_e32 vcc, v70, v122
	v_max_f32_e32 v70, v74, v74
	v_max_f32_e32 v74, v75, v75
	v_min_f32_e32 v70, 0x42a00000, v70
	v_min_f32_e32 v74, 0x42a00000, v74
	v_exp_f32_e32 v70, v70
	v_exp_f32_e32 v74, v74
	s_or_b64 vcc, s[42:43], vcc
	v_add_u32_e32 v75, 18, v148
	v_cndmask_b32_e32 v71, 1.0, v71, vcc
	v_cndmask_b32_e32 v73, 0, v69, vcc
	v_add_f32_e32 v69, 1.0, v70
	v_cmp_lt_i32_e32 vcc, v75, v122
	v_add_f32_e32 v75, 1.0, v74
	v_rcp_f32_e32 v69, v69
	v_rcp_f32_e32 v75, v75
	s_or_b64 vcc, s[42:43], vcc
	v_max_f32_e32 v77, v77, v77
	v_mul_f32_e32 v70, v70, v69
	v_cndmask_b32_e32 v160, 1.0, v69, vcc
	v_mul_f32_e32 v69, v74, v75
	v_add_u32_e32 v74, 19, v148
	v_cndmask_b32_e32 v70, 0, v70, vcc
	v_cmp_lt_i32_e32 vcc, v74, v122
	v_max_f32_e32 v74, v76, v76
	v_min_f32_e32 v74, 0x42a00000, v74
	v_exp_f32_e32 v74, v74
	v_min_f32_e32 v77, 0x42a00000, v77
	s_or_b64 vcc, s[42:43], vcc
	v_exp_f32_e32 v77, v77
	v_cndmask_b32_e32 v76, 0, v69, vcc
	v_add_f32_e32 v69, 1.0, v74
	v_rcp_f32_e32 v69, v69
	v_add_u32_e32 v137, 24, v148
	v_max_f32_e32 v78, v78, v78
	v_cndmask_b32_e32 v75, 1.0, v75, vcc
	v_cmp_lt_i32_e32 vcc, v137, v122
	v_add_f32_e32 v137, 1.0, v77
	v_min_f32_e32 v78, 0x42a00000, v78
	v_rcp_f32_e32 v137, v137
	v_exp_f32_e32 v78, v78
	v_mul_f32_e32 v74, v74, v69
	s_or_b64 vcc, s[42:43], vcc
	v_add_u32_e32 v161, 25, v148
	v_max_f32_e32 v79, v79, v79
	v_cndmask_b32_e32 v69, 1.0, v69, vcc
	v_cndmask_b32_e32 v74, 0, v74, vcc
	v_cmp_lt_i32_e32 vcc, v161, v122
	v_min_f32_e32 v79, 0x42a00000, v79
	s_or_b64 vcc, s[42:43], vcc
	v_exp_f32_e32 v79, v79
	v_mul_f32_e32 v77, v77, v137
	v_cndmask_b32_e32 v161, 1.0, v137, vcc
	v_add_f32_e32 v137, 1.0, v78
	v_rcp_f32_e32 v137, v137
	v_add_u32_e32 v162, 26, v148
	v_cndmask_b32_e32 v77, 0, v77, vcc
	v_cmp_lt_i32_e32 vcc, v162, v122
	v_add_f32_e32 v162, 1.0, v79
	v_rcp_f32_e32 v162, v162
	s_or_b64 vcc, s[42:43], vcc
	v_mul_f32_e32 v78, v78, v137
	v_cndmask_b32_e32 v163, 1.0, v137, vcc
	v_add_u32_e32 v137, 27, v148
	v_cndmask_b32_e32 v78, 0, v78, vcc
	v_cmp_lt_i32_e32 vcc, v137, v122
	v_mul_f32_e32 v65, v65, v154
	v_mul_f32_e32 v137, v156, v158
	s_or_b64 vcc, s[42:43], vcc
	v_mul_f32_e32 v137, v65, v137
	v_mul_f32_e32 v79, v79, v162
	v_cndmask_b32_e32 v148, 1.0, v162, vcc
	v_mov_b32_e32 v65, v137
	v_mov_b32_e32 v162, v137
	s_nop 1
	v_permlane32_swap_b32_e32 v65, v162
	v_cndmask_b32_e64 v65, v65, v162, s[0:1]
	v_mul_f32_e32 v67, v67, v71
	v_mul_f32_e32 v162, v160, v75
	v_mul_f32_e32 v67, v67, v162
	v_mov_b32_e32 v162, v67
	v_mov_b32_e32 v164, v67
	s_nop 1
	v_permlane32_swap_b32_e32 v162, v164
	v_cndmask_b32_e64 v162, v162, v164, s[0:1]
	v_mul_f32_e32 v69, v69, v161
	v_mul_f32_e32 v164, v163, v148
	v_mul_f32_e32 v69, v69, v164
	v_mov_b32_e32 v164, v69
	v_mov_b32_e32 v165, v69
	s_nop 1
	v_permlane32_swap_b32_e32 v164, v165
	v_cndmask_b32_e64 v164, v164, v165, s[0:1]
	v_cndmask_b32_e64 v165, 1.0, v164, s[0:1]
	v_mul_f32_e32 v69, v69, v164
	v_mul_f32_e32 v165, v146, v165
	v_mul_f32_e32 v69, v146, v69
	v_cndmask_b32_e64 v146, 1.0, v162, s[0:1]
	v_mul_f32_e32 v146, v146, v69
	v_mul_f32_e32 v148, v148, v165
	v_mul_f32_e32 v75, v75, v146
	v_mul_f32_e32 v163, v163, v148
	v_mul_f32_e32 v78, v78, v148
	v_mul_f32_e32 v148, v160, v75
	v_mul_f32_e32 v71, v71, v148
	v_mul_f32_e32 v67, v67, v162
	v_mul_f32_e32 v75, v70, v75
	v_mul_f32_e32 v148, v73, v148
	v_mul_f32_e32 v160, v72, v71
	v_pk_mul_f32 v[70:71], v[66:67], v[68:69]
	v_pk_mul_f32 v[72:73], v[136:137], v[64:65]
	v_mul_f32_e32 v76, v76, v146
	v_pk_mul_f32 v[72:73], v[72:73], v[70:71]
	v_cndmask_b32_e64 v146, 1.0, v65, s[0:1]
	v_mov_b32_e32 v65, v72
	v_mov_b32_e32 v67, v72
	s_nop 1
	v_permlane32_swap_b32_e32 v65, v67
	v_cndmask_b32_e64 v65, v65, v67, s[0:1]
	v_cndmask_b32_e64 v136, 1.0, v65, s[0:1]
	v_mul_f32_e32 v67, v146, v71
	v_mul_f32_e32 v136, v136, v73
	v_mul_f32_e32 v69, v158, v67
	v_mul_f32_e32 v68, v68, v136
	v_mul_f32_e32 v70, v156, v69
	v_mul_f32_e32 v66, v66, v68
	v_cndmask_b32_e32 v79, 0, v79, vcc
	v_mul_f32_e32 v161, v161, v163
	v_mul_f32_e32 v71, v154, v70
	v_mul_f32_e32 v64, v64, v66
	v_mul_f32_e32 v65, v72, v65
	v_mul_f32_e32 v79, v79, v165
	v_mul_f32_e32 v77, v77, v163
	v_mul_f32_e32 v74, v74, v161
	v_mul_f32_e32 v67, v159, v67
	v_mul_f32_e32 v69, v157, v69
	v_mul_f32_e32 v70, v155, v70
	v_mul_f32_e32 v71, v153, v71
	v_mul_f32_e32 v136, v151, v136
	v_mul_f32_e32 v68, v152, v68
	v_mul_f32_e32 v66, v150, v66
	v_mul_f32_e32 v64, v149, v64
	v_mul_f32_e32 v146, v65, v73
	v_cvt_pk_bf16_f32 v64, v64, v66
	v_cvt_pk_bf16_f32 v65, v68, v136
	v_cvt_pk_bf16_f32 v66, v71, v70
	v_cvt_pk_bf16_f32 v67, v69, v67
	v_cvt_pk_bf16_f32 v68, v160, v148
	v_cvt_pk_bf16_f32 v69, v75, v76
	v_cvt_pk_bf16_f32 v70, v74, v77
	v_cvt_pk_bf16_f32 v71, v78, v79
	v_cmp_gt_f32_e32 vcc, s55, v146
	s_waitcnt lgkmcnt(0)
	v_mfma_f32_32x32x16_bf16 v[48:63], v[116:119], v[64:67], v[48:63]
	ds_read_b64_tr_b16 v[72:73], v147 offset:17536
	ds_read_b64_tr_b16 v[74:75], v147 offset:20096
	v_mfma_f32_32x32x16_bf16 v[32:47], v[112:115], v[64:67], v[32:47]
	ds_read_b64_tr_b16 v[76:77], v147 offset:17600
	ds_read_b64_tr_b16 v[78:79], v147 offset:20160
	s_waitcnt lgkmcnt(0)
	v_mfma_f32_32x32x16_bf16 v[16:31], v[72:75], v[64:67], v[16:31]
	ds_read_b64_tr_b16 v[112:113], v147 offset:22528
	ds_read_b64_tr_b16 v[114:115], v147 offset:25088
	v_mfma_f32_32x32x16_bf16 v[0:15], v[76:79], v[64:67], v[0:15]
	ds_read_b64_tr_b16 v[72:73], v147 offset:22592
	ds_read_b64_tr_b16 v[74:75], v147 offset:25152
	s_waitcnt lgkmcnt(0)
	v_mfma_f32_32x32x16_bf16 v[48:63], v[112:115], v[68:71], v[48:63]
	ds_read_b64_tr_b16 v[64:65], v147 offset:22656
	ds_read_b64_tr_b16 v[66:67], v147 offset:25216
	v_mfma_f32_32x32x16_bf16 v[32:47], v[72:75], v[68:71], v[32:47]
	ds_read_b64_tr_b16 v[76:77], v147 offset:22720
	ds_read_b64_tr_b16 v[78:79], v147 offset:25280
	s_waitcnt lgkmcnt(0)
	v_mfma_f32_32x32x16_bf16 v[16:31], v[64:67], v[68:71], v[16:31]
	v_mfma_f32_32x32x16_bf16 v[0:15], v[76:79], v[68:71], v[0:15]
	s_cmp_eq_u64 vcc, exec
	s_cselect_b64 s[42:43], -1, 0
	s_and_saveexec_b64 s[44:45], s[4:5]
	s_cbranch_execnz .LBB0_349

.LBB0_681:
	s_ashr_i32 s51, s50, 31
	s_lshl_b64 s[54:55], s[50:51], 18
	s_add_u32 s54, s12, s54
	s_addc_u32 s55, s13, s55
	s_and_b64 s[4:5], s[4:5], exec
	s_cselect_b32 s51, s55, s59
	s_cselect_b32 s93, s54, s58
	s_add_u32 s94, s58, 0x100
	s_addc_u32 s95, s59, 0
	s_mov_b32 s96, -2
	v_mov_b64_e32 v[0:1], 0
	v_mov_b64_e32 v[2:3], 0
	v_mov_b64_e32 v[4:5], 0
	v_mov_b64_e32 v[6:7], 0
	v_mov_b64_e32 v[8:9], 0
	v_mov_b64_e32 v[10:11], 0
	v_mov_b64_e32 v[12:13], 0
	v_mov_b64_e32 v[14:15], 0
	v_mov_b64_e32 v[16:17], 0
	v_mov_b64_e32 v[18:19], 0
	v_mov_b64_e32 v[20:21], 0
	v_mov_b64_e32 v[22:23], 0
	v_mov_b64_e32 v[24:25], 0
	v_mov_b64_e32 v[26:27], 0
	v_mov_b64_e32 v[28:29], 0
	v_mov_b64_e32 v[30:31], 0
	v_mov_b64_e32 v[32:33], 0
	v_mov_b64_e32 v[34:35], 0
	v_mov_b64_e32 v[36:37], 0
	v_mov_b64_e32 v[38:39], 0
	v_mov_b64_e32 v[40:41], 0
	v_mov_b64_e32 v[42:43], 0
	v_mov_b64_e32 v[44:45], 0
	v_mov_b64_e32 v[46:47], 0
	v_mov_b64_e32 v[48:49], 0
	v_mov_b64_e32 v[50:51], 0
	v_mov_b64_e32 v[52:53], 0
	v_mov_b64_e32 v[54:55], 0
	v_mov_b64_e32 v[56:57], 0
	v_mov_b64_e32 v[58:59], 0
	v_mov_b64_e32 v[60:61], 0
	v_mov_b64_e32 v[62:63], 0
	v_mov_b64_e32 v[64:65], 0
	v_mov_b64_e32 v[66:67], 0
	v_mov_b64_e32 v[68:69], 0
	v_mov_b64_e32 v[70:71], 0
	v_mov_b64_e32 v[72:73], 0
	v_mov_b64_e32 v[74:75], 0
	v_mov_b64_e32 v[76:77], 0
	v_mov_b64_e32 v[78:79], 0
	v_mov_b64_e32 v[80:81], 0
	v_mov_b64_e32 v[82:83], 0
	v_mov_b64_e32 v[84:85], 0
	v_mov_b64_e32 v[86:87], 0
	v_mov_b64_e32 v[88:89], 0
	v_mov_b64_e32 v[90:91], 0
	v_mov_b64_e32 v[92:93], 0
	v_mov_b64_e32 v[94:95], 0
	v_mov_b64_e32 v[96:97], 0
	v_mov_b64_e32 v[98:99], 0
	v_mov_b64_e32 v[100:101], 0
	v_mov_b64_e32 v[102:103], 0
	v_mov_b64_e32 v[104:105], 0
	v_mov_b64_e32 v[106:107], 0
	v_mov_b64_e32 v[108:109], 0
	v_mov_b64_e32 v[110:111], 0
	v_mov_b64_e32 v[112:113], 0
	v_mov_b64_e32 v[114:115], 0
	v_mov_b64_e32 v[116:117], 0
	v_mov_b64_e32 v[118:119], 0
	v_mov_b64_e32 v[120:121], 0
	v_mov_b64_e32 v[122:123], 0
	v_mov_b64_e32 v[124:125], 0
	v_mov_b64_e32 v[126:127], 0

.LBB0_715:
	s_ashr_i32 s43, s42, 31
	s_lshl_b64 s[46:47], s[42:43], 18
	s_add_u32 s46, s12, s46
	s_addc_u32 s47, s13, s47
	s_and_b64 s[4:5], s[4:5], exec
	s_cselect_b32 s43, s47, s51
	s_cselect_b32 s86, s46, s50
	s_add_u32 s87, s50, 0x100
	s_addc_u32 s88, s51, 0
	s_mov_b32 s89, -2
	v_mov_b64_e32 v[0:1], 0
	v_mov_b64_e32 v[2:3], 0
	v_mov_b64_e32 v[4:5], 0
	v_mov_b64_e32 v[6:7], 0
	v_mov_b64_e32 v[8:9], 0
	v_mov_b64_e32 v[10:11], 0
	v_mov_b64_e32 v[12:13], 0
	v_mov_b64_e32 v[14:15], 0
	v_mov_b64_e32 v[16:17], 0
	v_mov_b64_e32 v[18:19], 0
	v_mov_b64_e32 v[20:21], 0
	v_mov_b64_e32 v[22:23], 0
	v_mov_b64_e32 v[24:25], 0
	v_mov_b64_e32 v[26:27], 0
	v_mov_b64_e32 v[28:29], 0
	v_mov_b64_e32 v[30:31], 0
	v_mov_b64_e32 v[32:33], 0
	v_mov_b64_e32 v[34:35], 0
	v_mov_b64_e32 v[36:37], 0
	v_mov_b64_e32 v[38:39], 0
	v_mov_b64_e32 v[40:41], 0
	v_mov_b64_e32 v[42:43], 0
	v_mov_b64_e32 v[44:45], 0
	v_mov_b64_e32 v[46:47], 0
	v_mov_b64_e32 v[48:49], 0
	v_mov_b64_e32 v[50:51], 0
	v_mov_b64_e32 v[52:53], 0
	v_mov_b64_e32 v[54:55], 0
	v_mov_b64_e32 v[56:57], 0
	v_mov_b64_e32 v[58:59], 0
	v_mov_b64_e32 v[60:61], 0
	v_mov_b64_e32 v[62:63], 0
	v_mov_b64_e32 v[64:65], 0
	v_mov_b64_e32 v[66:67], 0
	v_mov_b64_e32 v[68:69], 0
	v_mov_b64_e32 v[70:71], 0
	v_mov_b64_e32 v[72:73], 0
	v_mov_b64_e32 v[74:75], 0
	v_mov_b64_e32 v[76:77], 0
	v_mov_b64_e32 v[78:79], 0
	v_mov_b64_e32 v[80:81], 0
	v_mov_b64_e32 v[82:83], 0
	v_mov_b64_e32 v[84:85], 0
	v_mov_b64_e32 v[86:87], 0
	v_mov_b64_e32 v[88:89], 0
	v_mov_b64_e32 v[90:91], 0
	v_mov_b64_e32 v[92:93], 0
	v_mov_b64_e32 v[94:95], 0
	v_mov_b64_e32 v[96:97], 0
	v_mov_b64_e32 v[98:99], 0
	v_mov_b64_e32 v[100:101], 0
	v_mov_b64_e32 v[102:103], 0
	v_mov_b64_e32 v[104:105], 0
	v_mov_b64_e32 v[106:107], 0
	v_mov_b64_e32 v[108:109], 0
	v_mov_b64_e32 v[110:111], 0
	v_mov_b64_e32 v[112:113], 0
	v_mov_b64_e32 v[114:115], 0
	v_mov_b64_e32 v[116:117], 0
	v_mov_b64_e32 v[118:119], 0
	v_mov_b64_e32 v[120:121], 0
	v_mov_b64_e32 v[122:123], 0
	v_mov_b64_e32 v[124:125], 0
	v_mov_b64_e32 v[126:127], 0

.LBB0_792:
	s_add_i32 s26, s56, 1
	s_cmp_lg_u32 s26, s55
	s_cbranch_scc1 .Lgpf_skip
	s_mul_i32 s59, s38, 0x3c00000
	s_mul_hi_i32 s58, s38, 0x3c00000
	s_add_u32 s26, s30, s59
	s_addc_u32 s60, s31, s58
	s_lshl_b32 s58, s50, 7
	s_ashr_i32 s59, s58, 31
	s_lshl_b64 s[58:59], s[58:59], 1
	s_add_u32 s26, s26, s58
	s_addc_u32 s61, s60, s59
	s_add_u32 s60, s26, 0x9000a00
	s_addc_u32 s61, s61, 0
	v_mov_b64_e32 v[136:137], s[60:61]
	s_nop 1
	v_mad_i64_i32 v[136:137], s[60:61], v160, s49, v[136:137]
	v_lshlrev_b32_e32 v138, 1, v195
	v_mov_b32_e32 v139, 0
	v_lshl_add_u64 v[136:137], v[136:137], 0, v[138:139]
	global_load_dword v138, v[136:137], off
	global_load_dword v139, v[136:137], off offset:128

.LBB0_913:
	s_ashr_i32 s13, s12, 31
	s_lshl_b64 s[16:17], s[12:13], 20
	s_add_u32 s16, s90, s16
	s_addc_u32 s17, s91, s17
	s_and_b64 s[18:19], s[0:1], exec
	s_cselect_b32 s13, s17, s25
	s_cselect_b32 s43, s16, s24
	s_ashr_i32 s11, s10, 31
	s_lshl_b64 s[18:19], s[10:11], 20
	s_add_u32 s18, s20, s18
	s_addc_u32 s19, s21, s19
	s_and_b64 s[28:29], s[0:1], exec
	s_cselect_b32 s11, s19, s27
	s_cselect_b32 s44, s18, s26
	s_add_u32 s24, s24, 0x80080
	s_addc_u32 s25, s25, 0
	s_add_u32 s45, s26, 0x100
	s_addc_u32 s46, s27, 0
	s_mov_b32 s47, -2
	v_mov_b64_e32 v[0:1], 0
	v_mov_b64_e32 v[2:3], 0
	v_mov_b64_e32 v[4:5], 0
	v_mov_b64_e32 v[6:7], 0
	v_mov_b64_e32 v[8:9], 0
	v_mov_b64_e32 v[10:11], 0
	v_mov_b64_e32 v[12:13], 0
	v_mov_b64_e32 v[14:15], 0
	v_mov_b64_e32 v[16:17], 0
	v_mov_b64_e32 v[18:19], 0
	v_mov_b64_e32 v[20:21], 0
	v_mov_b64_e32 v[22:23], 0
	v_mov_b64_e32 v[24:25], 0
	v_mov_b64_e32 v[26:27], 0
	v_mov_b64_e32 v[28:29], 0
	v_mov_b64_e32 v[30:31], 0
	v_mov_b64_e32 v[32:33], 0
	v_mov_b64_e32 v[34:35], 0
	v_mov_b64_e32 v[36:37], 0
	v_mov_b64_e32 v[38:39], 0
	v_mov_b64_e32 v[40:41], 0
	v_mov_b64_e32 v[42:43], 0
	v_mov_b64_e32 v[44:45], 0
	v_mov_b64_e32 v[46:47], 0
	v_mov_b64_e32 v[48:49], 0
	v_mov_b64_e32 v[50:51], 0
	v_mov_b64_e32 v[52:53], 0
	v_mov_b64_e32 v[54:55], 0
	v_mov_b64_e32 v[56:57], 0
	v_mov_b64_e32 v[58:59], 0
	v_mov_b64_e32 v[60:61], 0
	v_mov_b64_e32 v[62:63], 0
	v_mov_b64_e32 v[64:65], 0
	v_mov_b64_e32 v[66:67], 0
	v_mov_b64_e32 v[68:69], 0
	v_mov_b64_e32 v[70:71], 0
	v_mov_b64_e32 v[72:73], 0
	v_mov_b64_e32 v[74:75], 0
	v_mov_b64_e32 v[76:77], 0
	v_mov_b64_e32 v[78:79], 0
	v_mov_b64_e32 v[80:81], 0
	v_mov_b64_e32 v[82:83], 0
	v_mov_b64_e32 v[84:85], 0
	v_mov_b64_e32 v[86:87], 0
	v_mov_b64_e32 v[88:89], 0
	v_mov_b64_e32 v[90:91], 0
	v_mov_b64_e32 v[92:93], 0
	v_mov_b64_e32 v[94:95], 0
	v_mov_b64_e32 v[96:97], 0
	v_mov_b64_e32 v[98:99], 0
	v_mov_b64_e32 v[100:101], 0
	v_mov_b64_e32 v[102:103], 0
	v_mov_b64_e32 v[104:105], 0
	v_mov_b64_e32 v[106:107], 0
	v_mov_b64_e32 v[108:109], 0
	v_mov_b64_e32 v[110:111], 0
	v_mov_b64_e32 v[112:113], 0
	v_mov_b64_e32 v[114:115], 0
	v_mov_b64_e32 v[116:117], 0
	v_mov_b64_e32 v[118:119], 0
	v_mov_b64_e32 v[120:121], 0
	v_mov_b64_e32 v[122:123], 0
	v_mov_b64_e32 v[124:125], 0
	v_mov_b64_e32 v[126:127], 0
